# v110 + own phase: 19 of a unit's 24 PART pieces are loaded before the causal attention loop (into registers the loop does not use) instead of after it
# speedup vs baseline: 1.0119x; 1.0006x over previous
.LBB0_928:
	s_add_i32 s96, s96, s64
	v_or_b32_e32 v138, s96, v131
	v_lshl_add_u64 v[32:33], s[84:85], 0, v[138:139]
	v_mad_u64_u32 v[34:35], s[38:39], v32, 12, s[60:61]
	v_mad_i32_i24 v35, v33, 12, v35
	global_load_dwordx3 v[128:130], v[34:35], off
	s_waitcnt vmcnt(0)
	s_waitcnt vmcnt(0) lgkmcnt(0)
	s_barrier
	v_add_u32_e32 v144, s96, v133
	v_lshl_add_u32 v144, v144, 1, v144
	v_mov_b32_e32 v138, v144
	v_lshlrev_b64 v[250:251], 8, v[138:139]
	v_lshl_add_u64 v[250:251], v[140:141], 0, v[250:251]
	global_load_dwordx4 v[194:197], v[250:251], off
	global_load_dwordx4 v[198:201], v[250:251], off offset:64
	global_load_dwordx4 v[178:181], v[250:251], off offset:128
	global_load_dwordx4 v[190:193], v[250:251], off offset:192
	v_add_u32_e32 v138, 48, v144
	v_lshlrev_b64 v[250:251], 8, v[138:139]
	v_lshl_add_u64 v[250:251], v[140:141], 0, v[250:251]
	global_load_dwordx4 v[202:205], v[250:251], off
	global_load_dwordx4 v[174:177], v[250:251], off offset:64
	global_load_dwordx4 v[182:185], v[250:251], off offset:128
	global_load_dwordx4 v[186:189], v[250:251], off offset:192
	v_add_u32_e32 v138, 1, v144
	v_lshlrev_b64 v[250:251], 8, v[138:139]
	v_lshl_add_u64 v[250:251], v[140:141], 0, v[250:251]
	global_load_dwordx4 v[206:209], v[250:251], off
	global_load_dwordx4 v[210:213], v[250:251], off offset:64
	global_load_dwordx4 v[214:217], v[250:251], off offset:128
	global_load_dwordx4 v[218:221], v[250:251], off offset:192
	v_add_u32_e32 v138, 49, v144
	v_lshlrev_b64 v[250:251], 8, v[138:139]
	v_lshl_add_u64 v[250:251], v[140:141], 0, v[250:251]
	global_load_dwordx4 v[222:225], v[250:251], off
	global_load_dwordx4 v[226:229], v[250:251], off offset:64
	global_load_dwordx4 v[230:233], v[250:251], off offset:128
	global_load_dwordx4 v[234:237], v[250:251], off offset:192
	v_add_u32_e32 v138, 2, v144
	v_lshlrev_b64 v[250:251], 8, v[138:139]
	v_lshl_add_u64 v[250:251], v[140:141], 0, v[250:251]
	global_load_dwordx4 v[238:241], v[250:251], off
	global_load_dwordx4 v[242:245], v[250:251], off offset:64
	global_load_dwordx4 v[246:249], v[250:251], off offset:128
	ds_write_b128 v155, v[0:3]
	ds_write_b128 v155, v[20:23] offset:1280
	ds_read_b128 v[80:83], v156
	ds_read_b128 v[84:87], v156 offset:32
	ds_write_b128 v155, v[4:7]
	ds_write_b128 v155, v[12:15] offset:1280
	ds_read_b128 v[88:91], v156
	ds_read_b128 v[92:95], v156 offset:32
	ds_write_b128 v155, v[8:11]
	ds_write_b128 v155, v[28:31] offset:1280
	ds_read_b128 v[96:99], v156
	ds_read_b128 v[100:103], v156 offset:32
	ds_write_b128 v155, v[16:19]
	ds_write_b128 v155, v[24:27] offset:1280
	ds_read_b128 v[104:107], v156
	ds_read_b128 v[108:111], v156 offset:32
	v_mov_b32_e32 v159, 0
	v_mov_b32_e32 v112, v154
	v_mov_b32_e32 v113, v153
	v_mov_b32_e32 v114, v152
	v_mov_b32_e32 v115, v151
	v_mov_b32_e32 v116, v150
	v_mov_b32_e32 v117, v149
	v_mov_b32_e32 v118, v148
	v_mov_b32_e32 v119, v147
	v_mov_b32_e32 v120, v146
	s_mov_b32 s38, s94
	v_mov_b32_e32 v0, 0
	v_mov_b32_e32 v1, v159
	v_mov_b32_e32 v2, v159
	v_mov_b32_e32 v3, v159
	v_mov_b32_e32 v4, v159
	v_mov_b32_e32 v5, v159
	v_mov_b32_e32 v6, v159
	v_mov_b32_e32 v7, v159
	v_mov_b32_e32 v8, v159
	v_mov_b32_e32 v9, v159
	v_mov_b32_e32 v10, v159
	v_mov_b32_e32 v11, v159
	v_mov_b32_e32 v12, v159
	v_mov_b32_e32 v13, v159
	v_mov_b32_e32 v14, v159
	v_mov_b32_e32 v15, v159
	v_mov_b32_e32 v16, 0
	v_mov_b32_e32 v17, v159
	v_mov_b32_e32 v18, v159
	v_mov_b32_e32 v19, v159
	v_mov_b32_e32 v20, v159
	v_mov_b32_e32 v21, v159
	v_mov_b32_e32 v22, v159
	v_mov_b32_e32 v23, v159
	v_mov_b32_e32 v24, v159
	v_mov_b32_e32 v25, v159
	v_mov_b32_e32 v26, v159
	v_mov_b32_e32 v27, v159
	v_mov_b32_e32 v28, v159
	v_mov_b32_e32 v29, v159
	v_mov_b32_e32 v30, v159
	v_mov_b32_e32 v31, v159
	v_mov_b32_e32 v32, 0
	v_mov_b32_e32 v33, v159
	v_mov_b32_e32 v34, v159
	v_mov_b32_e32 v35, v159
	v_mov_b32_e32 v36, v159
	v_mov_b32_e32 v37, v159
	v_mov_b32_e32 v38, v159
	v_mov_b32_e32 v39, v159
	v_mov_b32_e32 v40, v159
	v_mov_b32_e32 v41, v159
	v_mov_b32_e32 v42, v159
	v_mov_b32_e32 v43, v159
	v_mov_b32_e32 v44, v159
	v_mov_b32_e32 v45, v159
	v_mov_b32_e32 v46, v159
	v_mov_b32_e32 v47, v159
	v_mov_b32_e32 v48, 0
	v_mov_b32_e32 v49, v159
	v_mov_b32_e32 v50, v159
	v_mov_b32_e32 v51, v159
	v_mov_b32_e32 v52, v159
	v_mov_b32_e32 v53, v159
	v_mov_b32_e32 v54, v159
	v_mov_b32_e32 v55, v159
	v_mov_b32_e32 v56, v159
	v_mov_b32_e32 v57, v159
	v_mov_b32_e32 v58, v159
	v_mov_b32_e32 v59, v159
	v_mov_b32_e32 v60, v159
	v_mov_b32_e32 v61, v159
	v_mov_b32_e32 v62, v159
	v_mov_b32_e32 v63, v159
	s_branch .LBB0_930

.LBB0_932:
	s_waitcnt vmcnt(0)
	v_add_u32_e32 v64, s96, v133
	v_lshl_add_u32 v144, v64, 1, v64
	v_add_u32_e32 v138, 1, v144
	v_lshlrev_b64 v[64:65], 8, v[138:139]
	v_add_u32_e32 v138, 49, v144
	v_lshl_add_u64 v[64:65], v[140:141], 0, v[64:65]
	v_lshlrev_b64 v[66:67], 8, v[138:139]
	v_add_u32_e32 v138, 2, v144
	v_lshl_add_u64 v[66:67], v[140:141], 0, v[66:67]
	v_mov_b64_e32 v[120:121], v[206:207]
	v_mov_b64_e32 v[122:123], v[208:209]
	v_mov_b64_e32 v[112:113], v[210:211]
	v_mov_b64_e32 v[114:115], v[212:213]
	v_mov_b64_e32 v[124:125], v[222:223]
	v_mov_b64_e32 v[126:127], v[224:225]
	v_mov_b64_e32 v[116:117], v[226:227]
	v_mov_b64_e32 v[118:119], v[228:229]
	v_mov_b64_e32 v[104:105], v[214:215]
	v_mov_b64_e32 v[106:107], v[216:217]
	v_mov_b64_e32 v[96:97], v[218:219]
	v_mov_b64_e32 v[98:99], v[220:221]
	v_mov_b64_e32 v[108:109], v[230:231]
	v_mov_b64_e32 v[110:111], v[232:233]
	v_mov_b64_e32 v[100:101], v[234:235]
	v_mov_b64_e32 v[102:103], v[236:237]
	v_lshlrev_b64 v[64:65], 8, v[138:139]
	v_add_u32_e32 v138, 50, v144
	v_lshlrev_b64 v[66:67], 8, v[138:139]
	v_lshl_add_u64 v[64:65], v[140:141], 0, v[64:65]
	v_lshl_add_u64 v[68:69], v[140:141], 0, v[66:67]
	v_mov_b64_e32 v[88:89], v[238:239]
	v_mov_b64_e32 v[90:91], v[240:241]
	v_mov_b64_e32 v[80:81], v[242:243]
	v_mov_b64_e32 v[82:83], v[244:245]
	global_load_dwordx4 v[92:95], v[68:69], off
	global_load_dwordx4 v[84:87], v[68:69], off offset:64
	v_mov_b64_e32 v[72:73], v[246:247]
	v_mov_b64_e32 v[74:75], v[248:249]
	s_nop 0
	global_load_dwordx4 v[64:67], v[64:65], off offset:192
	s_nop 0
	global_load_dwordx4 v[76:79], v[68:69], off offset:128
	s_nop 0
	global_load_dwordx4 v[68:71], v[68:69], off offset:192
	ds_bpermute_b32 v161, v137, v159
	s_cmp_eq_u32 s97, 0
	s_cselect_b64 s[86:87], -1, 0
	s_and_b64 vcc, exec, s[86:87]
	v_add_u32_e32 v160, v135, v136
	s_cbranch_vccz .LBB0_935
	s_cmp_gt_u32 s97, 1
	s_cselect_b64 vcc, -1, 0
	s_cmp_lt_u32 s97, 2
	s_cbranch_scc0 .LBB0_936

.LBB0_935:
	v_add_u32_e32 v138, 48, v144
	v_mov_b32_e32 v145, v139
	v_lshlrev_b64 v[162:163], 8, v[138:139]
	v_lshlrev_b64 v[144:145], 8, v[144:145]
	v_lshl_add_u64 v[144:145], v[140:141], 0, v[144:145]
	v_mov_b64_e32 v[162:163], v[194:195]
	v_mov_b64_e32 v[164:165], v[196:197]
	v_mov_b64_e32 v[166:167], v[202:203]
	v_mov_b64_e32 v[168:169], v[204:205]
	v_mov_b64_e32 v[170:171], v[198:199]
	v_mov_b64_e32 v[172:173], v[200:201]
	s_nop 0
	s_nop 0
	s_waitcnt vmcnt(5)
	ds_write_b128 v160, v[162:165]
	s_waitcnt vmcnt(5)
	ds_write_b128 v157, v[166:169]
	ds_read2_b64 v[162:165], v158 offset1:2
	ds_read2_b64 v[166:169], v158 offset0:4 offset1:6
	s_waitcnt vmcnt(5)
	ds_write_b128 v160, v[170:173]
	s_waitcnt vmcnt(5)
	ds_write_b128 v157, v[174:177]
	ds_read2_b64 v[170:173], v158 offset1:2
	ds_read2_b64 v[174:177], v158 offset0:4 offset1:6
	s_waitcnt vmcnt(5)
	ds_write_b128 v160, v[178:181]
	s_waitcnt vmcnt(5)
	ds_write_b128 v157, v[182:185]
	ds_read2_b64 v[178:181], v158 offset1:2
	s_waitcnt lgkmcnt(8)
	v_lshlrev_b32_e32 v138, 16, v162
	v_add_f32_e32 v48, v48, v138
	s_waitcnt lgkmcnt(4)
	v_lshlrev_b32_e32 v138, 16, v170
	v_add_f32_e32 v32, v32, v138
	s_waitcnt lgkmcnt(0)
	v_lshlrev_b32_e32 v138, 16, v178
	v_and_b32_e32 v144, 0xffff0000, v162
	v_lshlrev_b32_e32 v145, 16, v163
	v_and_b32_e32 v162, 0xffff0000, v163
	v_lshlrev_b32_e32 v163, 16, v164
	v_and_b32_e32 v164, 0xffff0000, v164
	v_lshlrev_b32_e32 v182, 16, v165
	v_and_b32_e32 v165, 0xffff0000, v165
	v_add_f32_e32 v16, v16, v138
	v_and_b32_e32 v138, 0xffff0000, v178
	v_add_f32_e32 v51, v51, v162
	v_add_f32_e32 v52, v52, v163
	v_add_f32_e32 v53, v53, v164
	v_add_f32_e32 v55, v55, v165
	v_and_b32_e32 v162, 0xffff0000, v171
	v_lshlrev_b32_e32 v163, 16, v172
	v_and_b32_e32 v164, 0xffff0000, v172
	v_lshlrev_b32_e32 v165, 16, v173
	v_add_f32_e32 v17, v17, v138
	v_lshlrev_b32_e32 v138, 16, v179
	v_add_f32_e32 v35, v35, v162
	v_add_f32_e32 v36, v36, v163
	v_add_f32_e32 v37, v37, v164
	v_add_f32_e32 v38, v38, v165
	ds_read2_b64 v[162:165], v158 offset0:4 offset1:6
	v_add_f32_e32 v18, v18, v138
	v_and_b32_e32 v138, 0xffff0000, v179
	v_add_f32_e32 v19, v19, v138
	v_lshlrev_b32_e32 v138, 16, v180
	v_add_f32_e32 v20, v20, v138
	v_and_b32_e32 v138, 0xffff0000, v180
	v_add_f32_e32 v21, v21, v138
	v_lshlrev_b32_e32 v138, 16, v181
	v_add_f32_e32 v22, v22, v138
	v_and_b32_e32 v138, 0xffff0000, v181
	v_add_f32_e32 v23, v23, v138
	s_waitcnt lgkmcnt(0)
	v_lshlrev_b32_e32 v138, 16, v162
	v_lshlrev_b32_e32 v183, 16, v166
	v_and_b32_e32 v166, 0xffff0000, v166
	v_lshlrev_b32_e32 v184, 16, v167
	v_and_b32_e32 v167, 0xffff0000, v167
	v_lshlrev_b32_e32 v185, 16, v168
	v_and_b32_e32 v168, 0xffff0000, v168
	v_lshlrev_b32_e32 v194, 16, v169
	v_and_b32_e32 v169, 0xffff0000, v169
	v_add_f32_e32 v24, v24, v138
	v_and_b32_e32 v138, 0xffff0000, v162
	s_waitcnt vmcnt(5)
	ds_write_b128 v160, v[190:193]
	ds_write_b128 v157, v[186:189]
	v_add_f32_e32 v57, v57, v166
	v_add_f32_e32 v59, v59, v167
	v_add_f32_e32 v61, v61, v168
	v_add_f32_e32 v63, v63, v169
	v_and_b32_e32 v166, 0xffff0000, v173
	v_lshlrev_b32_e32 v167, 16, v174
	v_and_b32_e32 v168, 0xffff0000, v174
	v_lshlrev_b32_e32 v169, 16, v175
	v_add_f32_e32 v25, v25, v138
	v_lshlrev_b32_e32 v138, 16, v163
	v_add_f32_e32 v39, v39, v166
	v_add_f32_e32 v40, v40, v167
	v_add_f32_e32 v41, v41, v168
	v_add_f32_e32 v42, v42, v169
	v_add_f32_e32 v26, v26, v138
	v_and_b32_e32 v138, 0xffff0000, v163
	ds_read2_b64 v[166:169], v158 offset1:2
	v_add_f32_e32 v27, v27, v138
	v_lshlrev_b32_e32 v138, 16, v164
	v_add_f32_e32 v28, v28, v138
	v_and_b32_e32 v138, 0xffff0000, v164
	v_add_f32_e32 v29, v29, v138
	v_lshlrev_b32_e32 v138, 16, v165
	v_add_f32_e32 v30, v30, v138
	v_and_b32_e32 v138, 0xffff0000, v165
	v_add_f32_e32 v31, v31, v138
	s_waitcnt lgkmcnt(0)
	v_lshlrev_b32_e32 v138, 16, v166
	v_add_f32_e32 v0, v0, v138
	v_and_b32_e32 v138, 0xffff0000, v166
	v_add_f32_e32 v1, v1, v138
	v_lshlrev_b32_e32 v138, 16, v167
	ds_read2_b64 v[162:165], v158 offset0:4 offset1:6
	v_add_f32_e32 v2, v2, v138
	v_and_b32_e32 v138, 0xffff0000, v167
	v_add_f32_e32 v3, v3, v138
	v_lshlrev_b32_e32 v138, 16, v168
	v_add_f32_e32 v4, v4, v138
	v_and_b32_e32 v138, 0xffff0000, v168
	v_add_f32_e32 v5, v5, v138
	v_lshlrev_b32_e32 v138, 16, v169
	v_add_f32_e32 v6, v6, v138
	v_and_b32_e32 v138, 0xffff0000, v169
	v_add_f32_e32 v7, v7, v138
	s_waitcnt lgkmcnt(0)
	v_lshlrev_b32_e32 v138, 16, v162
	v_add_f32_e32 v8, v8, v138
	v_and_b32_e32 v138, 0xffff0000, v162
	v_add_f32_e32 v9, v9, v138
	v_lshlrev_b32_e32 v138, 16, v163
	v_add_f32_e32 v10, v10, v138
	v_and_b32_e32 v138, 0xffff0000, v163
	v_add_f32_e32 v11, v11, v138
	v_lshlrev_b32_e32 v138, 16, v164
	v_add_f32_e32 v12, v12, v138
	v_and_b32_e32 v138, 0xffff0000, v164
	v_add_f32_e32 v13, v13, v138
	v_lshlrev_b32_e32 v138, 16, v165
	v_add_f32_e32 v49, v49, v144
	v_add_f32_e32 v50, v50, v145
	v_and_b32_e32 v144, 0xffff0000, v170
	v_lshlrev_b32_e32 v145, 16, v171
	v_and_b32_e32 v170, 0xffff0000, v175
	v_lshlrev_b32_e32 v171, 16, v176
	v_and_b32_e32 v172, 0xffff0000, v176
	v_lshlrev_b32_e32 v173, 16, v177
	v_and_b32_e32 v174, 0xffff0000, v177
	v_add_f32_e32 v14, v14, v138
	v_and_b32_e32 v138, 0xffff0000, v165
	v_add_f32_e32 v54, v54, v182
	v_add_f32_e32 v56, v56, v183
	v_add_f32_e32 v58, v58, v184
	v_add_f32_e32 v60, v60, v185
	v_add_f32_e32 v62, v62, v194
	v_add_f32_e32 v33, v33, v144
	v_add_f32_e32 v34, v34, v145
	v_add_f32_e32 v43, v43, v170
	v_add_f32_e32 v44, v44, v171
	v_add_f32_e32 v45, v45, v172
	v_add_f32_e32 v46, v46, v173
	v_add_f32_e32 v47, v47, v174
	v_add_f32_e32 v15, v15, v138
	s_cmp_gt_u32 s97, 1
	s_cselect_b64 vcc, -1, 0
	s_cmp_lt_u32 s97, 2
	s_cbranch_scc1 .LBB0_934

.LBB0_937:
	s_waitcnt vmcnt(5)
	ds_write_b128 v160, v[88:91]
	s_waitcnt vmcnt(4)
	ds_write_b128 v157, v[92:95]
	ds_read2_b64 v[88:91], v158 offset1:2
	ds_read2_b64 v[92:95], v158 offset0:4 offset1:6
	ds_write_b128 v160, v[80:83]
	s_waitcnt vmcnt(3)
	ds_write_b128 v157, v[84:87]
	s_waitcnt lgkmcnt(3)
	v_lshlrev_b32_e32 v96, 16, v88
	v_and_b32_e32 v88, 0xffff0000, v88
	v_add_f32_e32 v49, v49, v88
	v_lshlrev_b32_e32 v88, 16, v89
	v_add_f32_e32 v50, v50, v88
	v_and_b32_e32 v88, 0xffff0000, v89
	v_add_f32_e32 v51, v51, v88
	v_lshlrev_b32_e32 v88, 16, v90
	v_add_f32_e32 v52, v52, v88
	v_and_b32_e32 v88, 0xffff0000, v90
	v_add_f32_e32 v53, v53, v88
	v_lshlrev_b32_e32 v88, 16, v91
	v_add_f32_e32 v54, v54, v88
	v_and_b32_e32 v88, 0xffff0000, v91
	v_add_f32_e32 v55, v55, v88
	s_waitcnt lgkmcnt(2)
	v_lshlrev_b32_e32 v88, 16, v92
	v_add_f32_e32 v56, v56, v88
	v_and_b32_e32 v88, 0xffff0000, v92
	v_add_f32_e32 v57, v57, v88
	v_lshlrev_b32_e32 v88, 16, v93
	v_add_f32_e32 v58, v58, v88
	v_and_b32_e32 v88, 0xffff0000, v93
	v_add_f32_e32 v59, v59, v88
	v_lshlrev_b32_e32 v88, 16, v94
	ds_read2_b64 v[80:83], v158 offset1:2
	ds_read2_b64 v[84:87], v158 offset0:4 offset1:6
	v_add_f32_e32 v60, v60, v88
	v_and_b32_e32 v88, 0xffff0000, v94
	v_add_f32_e32 v61, v61, v88
	v_lshlrev_b32_e32 v88, 16, v95
	v_add_f32_e32 v62, v62, v88
	v_and_b32_e32 v88, 0xffff0000, v95
	v_add_f32_e32 v63, v63, v88
	s_waitcnt lgkmcnt(1)
	v_lshlrev_b32_e32 v88, 16, v80
	v_and_b32_e32 v80, 0xffff0000, v80
	v_add_f32_e32 v33, v33, v80
	v_lshlrev_b32_e32 v80, 16, v81
	v_add_f32_e32 v34, v34, v80
	v_and_b32_e32 v80, 0xffff0000, v81
	v_add_f32_e32 v35, v35, v80
	v_lshlrev_b32_e32 v80, 16, v82
	v_add_f32_e32 v36, v36, v80
	v_and_b32_e32 v80, 0xffff0000, v82
	v_add_f32_e32 v37, v37, v80
	v_lshlrev_b32_e32 v80, 16, v83
	v_add_f32_e32 v38, v38, v80
	v_and_b32_e32 v80, 0xffff0000, v83
	v_add_f32_e32 v39, v39, v80
	s_waitcnt lgkmcnt(0)
	v_lshlrev_b32_e32 v80, 16, v84
	v_add_f32_e32 v40, v40, v80
	v_and_b32_e32 v80, 0xffff0000, v84
	v_add_f32_e32 v41, v41, v80
	v_lshlrev_b32_e32 v80, 16, v85
	s_waitcnt vmcnt(3)
	ds_write_b128 v160, v[72:75]
	s_waitcnt vmcnt(1)
	ds_write_b128 v157, v[76:79]
	v_add_f32_e32 v42, v42, v80
	v_and_b32_e32 v80, 0xffff0000, v85
	v_add_f32_e32 v43, v43, v80
	v_lshlrev_b32_e32 v80, 16, v86
	ds_read2_b64 v[72:75], v158 offset1:2
	ds_read2_b64 v[76:79], v158 offset0:4 offset1:6
	v_add_f32_e32 v44, v44, v80
	v_and_b32_e32 v80, 0xffff0000, v86
	v_add_f32_e32 v45, v45, v80
	v_lshlrev_b32_e32 v80, 16, v87
	v_add_f32_e32 v46, v46, v80
	v_and_b32_e32 v80, 0xffff0000, v87
	v_add_f32_e32 v47, v47, v80
	s_waitcnt lgkmcnt(1)
	v_lshlrev_b32_e32 v80, 16, v72
	v_and_b32_e32 v72, 0xffff0000, v72
	v_add_f32_e32 v17, v17, v72
	v_lshlrev_b32_e32 v72, 16, v73
	v_add_f32_e32 v18, v18, v72
	v_and_b32_e32 v72, 0xffff0000, v73
	v_add_f32_e32 v19, v19, v72
	v_lshlrev_b32_e32 v72, 16, v74
	v_add_f32_e32 v20, v20, v72
	v_and_b32_e32 v72, 0xffff0000, v74
	v_add_f32_e32 v21, v21, v72
	v_lshlrev_b32_e32 v72, 16, v75
	v_add_f32_e32 v22, v22, v72
	v_and_b32_e32 v72, 0xffff0000, v75
	v_add_f32_e32 v23, v23, v72
	s_waitcnt lgkmcnt(0)
	v_lshlrev_b32_e32 v72, 16, v76
	v_add_f32_e32 v24, v24, v72
	v_and_b32_e32 v72, 0xffff0000, v76
	v_add_f32_e32 v25, v25, v72
	v_lshlrev_b32_e32 v72, 16, v77
	ds_write_b128 v160, v[64:67]
	s_waitcnt vmcnt(0)
	ds_write_b128 v157, v[68:71]
	v_add_f32_e32 v26, v26, v72
	v_and_b32_e32 v72, 0xffff0000, v77
	v_add_f32_e32 v27, v27, v72
	v_lshlrev_b32_e32 v72, 16, v78
	ds_read2_b64 v[64:67], v158 offset1:2
	ds_read2_b64 v[68:71], v158 offset0:4 offset1:6
	v_add_f32_e32 v28, v28, v72
	v_and_b32_e32 v72, 0xffff0000, v78
	v_add_f32_e32 v29, v29, v72
	v_lshlrev_b32_e32 v72, 16, v79
	v_add_f32_e32 v30, v30, v72
	v_and_b32_e32 v72, 0xffff0000, v79
	v_add_f32_e32 v31, v31, v72
	s_waitcnt lgkmcnt(1)
	v_lshlrev_b32_e32 v72, 16, v64
	v_and_b32_e32 v64, 0xffff0000, v64
	v_add_f32_e32 v1, v1, v64
	v_lshlrev_b32_e32 v64, 16, v65
	v_add_f32_e32 v2, v2, v64
	v_and_b32_e32 v64, 0xffff0000, v65
	v_add_f32_e32 v3, v3, v64
	v_lshlrev_b32_e32 v64, 16, v66
	v_add_f32_e32 v4, v4, v64
	v_and_b32_e32 v64, 0xffff0000, v66
	v_add_f32_e32 v5, v5, v64
	v_lshlrev_b32_e32 v64, 16, v67
	v_add_f32_e32 v6, v6, v64
	v_and_b32_e32 v64, 0xffff0000, v67
	v_add_f32_e32 v7, v7, v64
	s_waitcnt lgkmcnt(0)
	v_lshlrev_b32_e32 v64, 16, v68
	v_add_f32_e32 v8, v8, v64
	v_and_b32_e32 v64, 0xffff0000, v68
	v_add_f32_e32 v9, v9, v64
	v_lshlrev_b32_e32 v64, 16, v69
	v_add_f32_e32 v10, v10, v64
	v_and_b32_e32 v64, 0xffff0000, v69
	v_add_f32_e32 v11, v11, v64
	v_lshlrev_b32_e32 v64, 16, v70
	v_add_f32_e32 v12, v12, v64
	v_and_b32_e32 v64, 0xffff0000, v70
	v_add_f32_e32 v13, v13, v64
	v_lshlrev_b32_e32 v64, 16, v71
	v_add_f32_e32 v14, v14, v64
	v_and_b32_e32 v64, 0xffff0000, v71
	v_add_f32_e32 v48, v48, v96
	v_add_f32_e32 v32, v32, v88
	v_add_f32_e32 v16, v16, v80
	v_add_f32_e32 v0, v0, v72
	v_add_f32_e32 v15, v15, v64
	s_branch .LBB0_925
